# DA loop: in the last two tiles of a workgroup's first DA unit the idle staging registers prefetch (touch) the first K/V tile of its second unit into L2
# baseline (speedup 1.0000x reference)
; __device__ void da_unit(char* lds, const Params& p, int layer, int unit) {
;     ...
;         const int t0 = tile_of(0);
; #pragma unroll
;         for (int j = 0; j < 4; ++j) { rk[j] = *(const u32x4*)(Kg + (size_t)t0 * 16384 + j * 4096); rv[j] = *(const u32x4*)(Vg + (size_t)t0 * 16384 + j * 4096); }
;     ...
;         if (it + 1 < NT) {
; #pragma unroll
;             for (int j = 0; j < 4; ++j) rk[j] = *(const u32x4*)(Kg + (size_t)tn * 16384 + j * 4096);
;         }
.Lda_nok:
	s_cmp_lt_u32 s4, 14
	s_cbranch_scc1 .Lda_nopf
	s_cmpk_gt_u32 s21, 0xff
	s_cbranch_scc1 .Lda_nopf
	s_mov_b32 s18, 0x100000
	s_mov_b32 s19, 0
	s_cmp_eq_u32 s4, 14
	s_cbranch_scc0 .Lda_pfv
	v_lshl_add_u64 v[156:157], v[164:165], 0, s[18:19]
	global_load_dword v130, v[156:157], off
	s_add_u32 s18, s18, 0x2000
	v_lshl_add_u64 v[156:157], v[164:165], 0, s[18:19]
	global_load_dword v131, v[156:157], off
	s_add_u32 s18, s18, 0x2000
	v_lshl_add_u64 v[156:157], v[164:165], 0, s[18:19]
	global_load_dword v132, v[156:157], off
	s_add_u32 s18, s18, 0x2000
	v_lshl_add_u64 v[156:157], v[164:165], 0, s[18:19]
	global_load_dword v133, v[156:157], off
	s_branch .Lda_nopf
.Lda_pfv:
	v_lshl_add_u64 v[156:157], v[166:167], 0, s[18:19]
	global_load_dword v134, v[156:157], off
	s_add_u32 s18, s18, 0x2000
	v_lshl_add_u64 v[156:157], v[166:167], 0, s[18:19]
	global_load_dword v135, v[156:157], off
	s_add_u32 s18, s18, 0x2000
	v_lshl_add_u64 v[156:157], v[166:167], 0, s[18:19]
	global_load_dword v136, v[156:157], off
	s_add_u32 s18, s18, 0x2000
	v_lshl_add_u64 v[156:157], v[166:167], 0, s[18:19]
	global_load_dword v137, v[156:157], off
